# MLA compute block: 6-deep fragment ring (v[44:47] freed), one lgkmcnt wait per three reads (18 waits)
# baseline (speedup 1.0000x reference)
.LBB0_1457:
	s_or_saveexec_b64 s[34:35], s[14:15]
	v_mov_b32_e32 v100, 0
	v_mov_b32_e32 v104, 0
	s_xor_b64 exec, exec, s[34:35]
	s_cbranch_execz .LBB0_1505
	s_and_saveexec_b64 s[6:7], vcc
	s_xor_b64 s[6:7], exec, s[6:7]
	v_lshlrev_b64 v[24:25], 12, v[24:25]
	v_lshl_add_u64 v[24:25], s[82:83], 0, v[24:25]
	v_lshl_add_u64 v[24:25], v[118:119], 1, v[24:25]
	v_lshl_add_u64 v[26:27], v[24:25], 0, s[70:71]
	s_andn2_saveexec_b64 s[6:7], s[6:7]
	v_lshlrev_b64 v[24:25], 10, v[24:25]
	v_lshl_add_u64 v[24:25], v[144:145], 0, v[24:25]
	v_lshl_add_u64 v[26:27], v[118:119], 1, v[24:25]
	s_or_b64 exec, exec, s[6:7]
	global_load_dwordx4 v[24:27], v[26:27], off
	v_or_b32_e32 v30, v52, v209
	v_cmp_gt_i32_e64 s[6:7], 8, v28
	v_cmp_lt_i32_e32 vcc, 7, v28
	v_ashrrev_i32_e32 v31, 31, v30
	s_and_saveexec_b64 s[8:9], vcc
	s_xor_b64 s[8:9], exec, s[8:9]
	v_lshlrev_b64 v[28:29], 12, v[30:31]
	v_lshl_add_u64 v[28:29], s[82:83], 0, v[28:29]
	v_lshl_add_u64 v[28:29], v[120:121], 1, v[28:29]
	v_lshl_add_u64 v[28:29], v[28:29], 0, s[70:71]
	s_andn2_saveexec_b64 s[8:9], s[8:9]
	v_lshlrev_b64 v[28:29], 10, v[30:31]
	v_lshl_add_u64 v[28:29], v[144:145], 0, v[28:29]
	v_lshl_add_u64 v[28:29], v[120:121], 1, v[28:29]
	s_or_b64 exec, exec, s[8:9]
	global_load_dwordx4 v[28:31], v[28:29], off
	v_or_b32_e32 v34, v52, v210
	v_cmp_gt_i32_e64 s[8:9], 8, v32
	v_cmp_lt_i32_e32 vcc, 7, v32
	v_ashrrev_i32_e32 v35, 31, v34
	s_and_saveexec_b64 s[10:11], vcc
	s_xor_b64 s[10:11], exec, s[10:11]
	v_lshlrev_b64 v[32:33], 12, v[34:35]
	v_lshl_add_u64 v[32:33], s[82:83], 0, v[32:33]
	v_lshl_add_u64 v[32:33], v[122:123], 1, v[32:33]
	v_lshl_add_u64 v[32:33], v[32:33], 0, s[70:71]
	s_andn2_saveexec_b64 s[10:11], s[10:11]
	v_lshlrev_b64 v[32:33], 10, v[34:35]
	v_lshl_add_u64 v[32:33], v[144:145], 0, v[32:33]
	v_lshl_add_u64 v[32:33], v[122:123], 1, v[32:33]
	s_or_b64 exec, exec, s[10:11]
	global_load_dwordx4 v[32:35], v[32:33], off
	v_or_b32_e32 v38, v52, v149
	v_cmp_gt_i32_e64 s[10:11], 8, v36
	v_cmp_lt_i32_e32 vcc, 7, v36
	v_ashrrev_i32_e32 v39, 31, v38
	s_and_saveexec_b64 s[12:13], vcc
	s_xor_b64 s[12:13], exec, s[12:13]
	v_lshlrev_b64 v[36:37], 12, v[38:39]
	v_lshl_add_u64 v[36:37], s[82:83], 0, v[36:37]
	v_lshl_add_u64 v[36:37], v[44:45], 1, v[36:37]
	v_lshl_add_u64 v[36:37], v[36:37], 0, s[70:71]
	s_andn2_saveexec_b64 s[12:13], s[12:13]
	v_lshlrev_b64 v[36:37], 10, v[38:39]
	v_lshl_add_u64 v[36:37], v[144:145], 0, v[36:37]
	v_lshl_add_u64 v[36:37], v[44:45], 1, v[36:37]
	s_or_b64 exec, exec, s[12:13]
	global_load_dwordx4 v[36:39], v[36:37], off
	v_cmp_gt_i32_e64 s[12:13], 8, v42
	v_cmp_lt_i32_e32 vcc, 7, v42
	v_or_b32_e32 v42, v52, v152
	v_ashrrev_i32_e32 v43, 31, v42
	s_and_saveexec_b64 s[14:15], vcc
	s_xor_b64 s[14:15], exec, s[14:15]
	v_lshlrev_b64 v[40:41], 12, v[42:43]
	v_lshl_add_u64 v[40:41], s[82:83], 0, v[40:41]
	v_lshl_add_u64 v[40:41], v[46:47], 1, v[40:41]
	v_lshl_add_u64 v[40:41], v[40:41], 0, s[70:71]
	s_andn2_saveexec_b64 s[14:15], s[14:15]
	v_lshlrev_b64 v[40:41], 10, v[42:43]
	v_lshl_add_u64 v[40:41], v[144:145], 0, v[40:41]
	v_lshl_add_u64 v[40:41], v[46:47], 1, v[40:41]
	s_or_b64 exec, exec, s[14:15]
	global_load_dwordx4 v[40:43], v[40:41], off
	v_or_b32_e32 v50, v52, v153
	v_cmp_gt_i32_e64 s[14:15], 8, v48
	v_cmp_lt_i32_e32 vcc, 7, v48
	v_ashrrev_i32_e32 v51, 31, v50
	s_and_saveexec_b64 s[16:17], vcc
	s_xor_b64 s[16:17], exec, s[16:17]
	v_lshlrev_b64 v[48:49], 12, v[50:51]
	v_lshl_add_u64 v[48:49], s[82:83], 0, v[48:49]
	v_lshl_add_u64 v[48:49], v[102:103], 1, v[48:49]
	v_lshl_add_u64 v[48:49], v[48:49], 0, s[70:71]
	s_andn2_saveexec_b64 s[16:17], s[16:17]
	v_lshlrev_b64 v[48:49], 10, v[50:51]
	v_lshl_add_u64 v[48:49], v[144:145], 0, v[48:49]
	v_lshl_add_u64 v[48:49], v[102:103], 1, v[48:49]
	s_or_b64 exec, exec, s[16:17]
	v_and_b32_e32 v155, 0x7e, v105
	v_or_b32_e32 v54, v155, v52
	v_or_b32_e32 v52, 1, v54
	v_ashrrev_i32_e32 v55, 31, v54
	v_lshlrev_b32_e32 v68, 4, v53
	v_ashrrev_i32_e32 v53, 31, v52
	v_lshlrev_b64 v[56:57], 10, v[54:55]
	v_lshlrev_b64 v[52:53], 10, v[52:53]
	v_lshl_add_u64 v[56:57], v[144:145], 0, v[56:57]
	v_mov_b32_e32 v69, v129
	v_lshl_add_u64 v[52:53], v[144:145], 0, v[52:53]
	v_lshl_add_u64 v[56:57], v[56:57], 0, v[68:69]
	v_lshl_add_u64 v[64:65], v[52:53], 0, v[68:69]
	global_load_dwordx4 v[48:51], v[48:49], off
	s_nop 0
	global_load_dwordx4 v[52:55], v[56:57], off offset:128
	s_nop 0
	global_load_dwordx4 v[56:59], v[56:57], off offset:192
	s_nop 0
	global_load_dwordx4 v[60:63], v[64:65], off offset:128
	s_nop 0
	global_load_dwordx4 v[64:67], v[64:65], off offset:192
	v_lshrrev_b32_e32 v70, 3, v101
	v_and_b32_e32 v70, 24, v70
	v_mul_u32_u24_e32 v70, 0x120, v70
	v_and_b32_e32 v71, 2, v155
	v_lshlrev_b32_e32 v71, 1, v71
	v_and_b32_e32 v73, 12, v155
	v_lshl_or_b32 v71, v73, 2, v71
	v_and_b32_e32 v73, 0x60, v155
	v_lshl_or_b32 v71, v73, 1, v71
	v_and_b32_e32 v73, 16, v155
	v_lshrrev_b32_e32 v73, 1, v73
	v_or_b32_e32 v71, v71, v73
	v_add3_u32 v159, s33, v70, v71
	v_mul_u32_u24_e32 v70, 0x90, v133
	v_lshlrev_b32_e32 v70, 1, v70
	v_lshlrev_b64 v[44:45], 1, v[44:45]
	v_lshlrev_b32_e32 v128, 2, v126
	v_add_u32_e32 v156, 0x8080, v127
	v_add3_u32 v160, s33, v70, v125
	v_add_u32_e32 v160, v160, v125
	v_or_b32_e32 v70, 32, v133
	v_or_b32_e32 v71, 64, v133
	v_lshl_add_u64 v[126:127], s[82:83], 0, v[44:45]
	v_lshl_add_u64 v[134:135], v[144:145], 0, v[44:45]
	v_lshlrev_b64 v[44:45], 1, v[46:47]
	v_mul_u32_u24_e32 v73, 0xd0, v70
	v_mul_u32_u24_e32 v74, 0xd0, v71
	v_lshlrev_b64 v[70:71], 1, v[118:119]
	v_lshl_add_u64 v[136:137], s[82:83], 0, v[44:45]
	v_lshl_add_u64 v[138:139], v[144:145], 0, v[44:45]
	v_sub_u32_e32 v248, 0x87f, v148
	v_lshl_add_u64 v[112:113], s[82:83], 0, v[70:71]
	v_lshl_add_u64 v[114:115], v[144:145], 0, v[70:71]
	v_lshlrev_b64 v[70:71], 1, v[120:121]
	v_lshrrev_b32_e32 v248, 8, v248
	v_mul_u32_u24_e32 v72, 0xe0, v133
	v_lshl_add_u64 v[118:119], s[82:83], 0, v[70:71]
	v_lshl_add_u64 v[120:121], v[144:145], 0, v[70:71]
	v_lshlrev_b64 v[70:71], 1, v[122:123]
	v_add_u32_e32 v249, 4, v248
	v_readlane_b32 s16, v253, 26
	v_mov_b32_e32 v80, 0
	v_add_u32_e32 v157, 0xffffff80, v124
	v_lshl_add_u32 v158, v102, 1, v106
	v_lshl_add_u64 v[122:123], s[82:83], 0, v[70:71]
	v_lshl_add_u64 v[124:125], v[144:145], 0, v[70:71]
	v_lshl_add_u64 v[140:141], v[102:103], 1, s[82:83]
	v_lshl_add_u64 v[142:143], v[102:103], 1, v[144:145]
	v_and_b32_e32 v163, 28, v249
	v_lshl_add_u64 v[144:145], v[144:145], 0, v[68:69]
	v_add_u32_e32 v164, s16, v105
	v_add_u32_e32 v164, 0xc00, v164
	s_mov_b32 s53, 0
	v_add_u32_e32 v165, v107, v72
	v_subrev_u32_e32 v161, s33, v146
	v_mul_u32_u24_e32 v161, 0x4ec5, v161
	v_lshrrev_b32_e32 v161, 22, v161
	v_lshl_add_u32 v161, v161, 4, v146
	v_subrev_u32_e32 v162, s33, v147
	v_mul_u32_u24_e32 v162, 0x4ec5, v162
	v_lshrrev_b32_e32 v162, 22, v162
	v_lshl_add_u32 v162, v162, 4, v147
	v_subrev_u32_e32 v166, s33, v150
	v_mul_u32_u24_e32 v166, 0x4ec5, v166
	v_lshrrev_b32_e32 v166, 22, v166
	v_lshl_add_u32 v166, v166, 4, v150
	v_subrev_u32_e32 v167, s33, v151
	v_mul_u32_u24_e32 v167, 0x4ec5, v167
	v_lshrrev_b32_e32 v167, 22, v167
	v_lshl_add_u32 v167, v167, 4, v151
	v_subrev_u32_e32 v188, s33, v154
	v_mul_u32_u24_e32 v188, 0x4ec5, v188
	v_lshrrev_b32_e32 v188, 22, v188
	v_lshl_add_u32 v188, v188, 4, v154
	v_subrev_u32_e32 v211, s33, v158
	v_mul_u32_u24_e32 v211, 0x4ec5, v211
	v_lshrrev_b32_e32 v211, 22, v211
	v_lshl_add_u32 v211, v211, 4, v158
	v_mov_b32_e32 v81, v80
	v_mov_b32_e32 v82, v80
	v_mov_b32_e32 v83, v80
	v_mov_b32_e32 v76, v80
	v_mov_b32_e32 v77, v80
	v_mov_b32_e32 v78, v80
	v_mov_b32_e32 v79, v80
	v_mov_b32_e32 v72, v80
	v_mov_b32_e32 v73, v80
	v_mov_b32_e32 v74, v80
	v_mov_b32_e32 v75, v80
	v_mov_b32_e32 v68, v80
	v_mov_b32_e32 v69, v80
	v_mov_b32_e32 v70, v80
	v_mov_b32_e32 v71, v80
	v_mov_b32_e32 v96, v80
	v_mov_b32_e32 v97, v80
	v_mov_b32_e32 v98, v80
	v_mov_b32_e32 v99, v80
	v_mov_b32_e32 v92, v80
	v_mov_b32_e32 v93, v80
	v_mov_b32_e32 v94, v80
	v_mov_b32_e32 v95, v80
	v_mov_b32_e32 v88, v80
	v_mov_b32_e32 v89, v80
	v_mov_b32_e32 v90, v80
	v_mov_b32_e32 v91, v80
	v_mov_b32_e32 v84, v80
	v_mov_b32_e32 v85, v80
	v_mov_b32_e32 v86, v80
	v_mov_b32_e32 v87, v80
	v_mov_b32_e32 v104, v80
	v_mov_b32_e32 v105, v80
	v_mov_b32_e32 v106, v80
	v_mov_b32_e32 v107, v80
	v_mov_b32_e32 v100, v80
	v_mov_b32_e32 v101, v80
	v_mov_b32_e32 v102, v80
	v_mov_b32_e32 v103, v80
	v_readfirstlane_b32 s60, v131
	s_nop 0
	s_cmp_lt_u32 s60, 0x100
	s_cbranch_scc1 .Lmla_stg_pre
	s_barrier

.LBB0_1483:
	s_add_i32 s53, s53, 1
	ds_read_b128 v[212:215], v165
	ds_read_b128 v[216:219], v165 offset:64
	ds_read_b128 v[220:223], v165 offset:128
	ds_read_b128 v[224:227], v165 offset:3584
	ds_read_b128 v[228:231], v165 offset:3648
	ds_read_b128 v[44:47], v165 offset:3712
	s_waitcnt lgkmcnt(3)
	v_mfma_f32_16x16x32_bf16 v[232:235], v[212:215], v[0:3], 0
	v_mfma_f32_16x16x32_bf16 v[240:243], v[212:215], v[12:15], 0
	ds_read_b128 v[212:215], v165 offset:7168
	v_mfma_f32_16x16x32_bf16 v[232:235], v[216:219], v[4:7], v[232:235]
	v_mfma_f32_16x16x32_bf16 v[240:243], v[216:219], v[16:19], v[240:243]
	ds_read_b128 v[216:219], v165 offset:7232
	v_mfma_f32_16x16x32_bf16 v[232:235], v[220:223], v[8:11], v[232:235]
	v_mfma_f32_16x16x32_bf16 v[240:243], v[220:223], v[20:23], v[240:243]
	ds_read_b128 v[220:223], v165 offset:7296
	s_waitcnt lgkmcnt(3)
	v_mfma_f32_16x16x32_bf16 v[236:239], v[224:227], v[0:3], 0
	v_mfma_f32_16x16x32_bf16 v[244:247], v[224:227], v[12:15], 0
	ds_read_b128 v[224:227], v165 offset:10752
	v_mfma_f32_16x16x32_bf16 v[236:239], v[228:231], v[4:7], v[236:239]
	v_mfma_f32_16x16x32_bf16 v[244:247], v[228:231], v[16:19], v[244:247]
	ds_read_b128 v[228:231], v165 offset:10816
	v_mfma_f32_16x16x32_bf16 v[236:239], v[44:47], v[8:11], v[236:239]
	v_exp_f32_e32 v232, v232
	v_mfma_f32_16x16x32_bf16 v[244:247], v[44:47], v[20:23], v[244:247]
	v_exp_f32_e32 v233, v233
	ds_read_b128 v[44:47], v165 offset:10880
	s_waitcnt lgkmcnt(3)
	v_mfma_f32_16x16x32_bf16 v[168:171], v[212:215], v[0:3], 0
	v_exp_f32_e32 v234, v234
	v_mfma_f32_16x16x32_bf16 v[176:179], v[212:215], v[12:15], 0
	v_exp_f32_e32 v235, v235
	ds_read_b128 v[212:215], v160 offset:28672
	v_mfma_f32_16x16x32_bf16 v[168:171], v[216:219], v[4:7], v[168:171]
	v_cvt_pk_bf16_f32 v232, v232, v233
	v_cvt_pk_bf16_f32 v233, v234, v235
	v_mfma_f32_16x16x32_bf16 v[176:179], v[216:219], v[16:19], v[176:179]
	v_exp_f32_e32 v240, v240
	ds_read_b128 v[216:219], v160 offset:33280
	v_mfma_f32_16x16x32_bf16 v[168:171], v[220:223], v[8:11], v[168:171]
	v_exp_f32_e32 v241, v241
	v_mfma_f32_16x16x32_bf16 v[176:179], v[220:223], v[20:23], v[176:179]
	v_exp_f32_e32 v242, v242
	ds_read_b128 v[220:223], v160 offset:37888
	s_waitcnt lgkmcnt(3)
	v_mfma_f32_16x16x32_bf16 v[172:175], v[224:227], v[0:3], 0
	v_exp_f32_e32 v243, v243
	v_mfma_f32_16x16x32_bf16 v[108:111], v[224:227], v[12:15], 0
	v_cvt_pk_bf16_f32 v240, v240, v241
	v_cvt_pk_bf16_f32 v241, v242, v243
	ds_read_b128 v[224:227], v160 offset:42496
	v_mfma_f32_16x16x32_bf16 v[172:175], v[228:231], v[4:7], v[172:175]
	v_exp_f32_e32 v236, v236
	v_mfma_f32_16x16x32_bf16 v[108:111], v[228:231], v[16:19], v[108:111]
	v_exp_f32_e32 v237, v237
	ds_read_b128 v[228:231], v160 offset:47104
	v_mfma_f32_16x16x32_bf16 v[172:175], v[44:47], v[8:11], v[172:175]
	v_exp_f32_e32 v238, v238
	v_mfma_f32_16x16x32_bf16 v[108:111], v[44:47], v[20:23], v[108:111]
	v_exp_f32_e32 v239, v239
	ds_read_b128 v[44:47], v165 offset:14336
	s_waitcnt lgkmcnt(3)
	v_cvt_pk_bf16_f32 v234, v236, v237
	v_cvt_pk_bf16_f32 v235, v238, v239
	v_exp_f32_e32 v244, v244
	v_exp_f32_e32 v245, v245
	v_mfma_f32_16x16x32_bf16 v[84:87], v[212:215], v[232:235], v[84:87]
	v_exp_f32_e32 v246, v246
	v_exp_f32_e32 v247, v247
	v_cvt_pk_bf16_f32 v242, v244, v245
	v_cvt_pk_bf16_f32 v243, v246, v247
	v_exp_f32_e32 v168, v168
	v_exp_f32_e32 v169, v169
	v_mfma_f32_16x16x32_bf16 v[68:71], v[212:215], v[240:243], v[68:71]
	v_exp_f32_e32 v170, v170
	ds_read_b128 v[212:215], v165 offset:14400
	v_mfma_f32_16x16x32_bf16 v[88:91], v[216:219], v[232:235], v[88:91]
	v_exp_f32_e32 v171, v171
	v_mfma_f32_16x16x32_bf16 v[72:75], v[216:219], v[240:243], v[72:75]
	v_cvt_pk_bf16_f32 v168, v168, v169
	v_cvt_pk_bf16_f32 v169, v170, v171
	ds_read_b128 v[216:219], v165 offset:14464
	v_mfma_f32_16x16x32_bf16 v[92:95], v[220:223], v[232:235], v[92:95]
	v_exp_f32_e32 v176, v176
	v_mfma_f32_16x16x32_bf16 v[76:79], v[220:223], v[240:243], v[76:79]
	v_exp_f32_e32 v177, v177
	ds_read_b128 v[220:223], v165 offset:17920
	s_waitcnt lgkmcnt(3)
	v_mfma_f32_16x16x32_bf16 v[96:99], v[224:227], v[232:235], v[96:99]
	v_exp_f32_e32 v178, v178
	v_mfma_f32_16x16x32_bf16 v[80:83], v[224:227], v[240:243], v[80:83]
	v_exp_f32_e32 v179, v179
	ds_read_b128 v[224:227], v165 offset:17984
	v_mfma_f32_16x16x32_bf16 v[104:107], v[228:231], v[232:235], v[104:107]
	v_cvt_pk_bf16_f32 v176, v176, v177
	v_cvt_pk_bf16_f32 v177, v178, v179
	v_mfma_f32_16x16x32_bf16 v[100:103], v[228:231], v[240:243], v[100:103]
	v_exp_f32_e32 v172, v172
	ds_read_b128 v[228:231], v165 offset:18048
	v_mfma_f32_16x16x32_bf16 v[232:235], v[44:47], v[0:3], 0
	v_exp_f32_e32 v173, v173
	v_mfma_f32_16x16x32_bf16 v[240:243], v[44:47], v[12:15], 0
	v_exp_f32_e32 v174, v174
	ds_read_b128 v[44:47], v160 offset:28736
	s_waitcnt lgkmcnt(3)
	v_mfma_f32_16x16x32_bf16 v[232:235], v[212:215], v[4:7], v[232:235]
	v_exp_f32_e32 v175, v175
	v_mfma_f32_16x16x32_bf16 v[240:243], v[212:215], v[16:19], v[240:243]
	v_cvt_pk_bf16_f32 v170, v172, v173
	v_cvt_pk_bf16_f32 v171, v174, v175
	ds_read_b128 v[212:215], v160 offset:33344
	v_mfma_f32_16x16x32_bf16 v[232:235], v[216:219], v[8:11], v[232:235]
	v_exp_f32_e32 v108, v108
	v_mfma_f32_16x16x32_bf16 v[240:243], v[216:219], v[20:23], v[240:243]
	v_exp_f32_e32 v109, v109
	ds_read_b128 v[216:219], v160 offset:37952
	v_mfma_f32_16x16x32_bf16 v[236:239], v[220:223], v[0:3], 0
	v_exp_f32_e32 v110, v110
	v_mfma_f32_16x16x32_bf16 v[244:247], v[220:223], v[12:15], 0
	v_exp_f32_e32 v111, v111
	ds_read_b128 v[220:223], v160 offset:42560
	s_waitcnt lgkmcnt(3)
	v_mfma_f32_16x16x32_bf16 v[236:239], v[224:227], v[4:7], v[236:239]
	v_cvt_pk_bf16_f32 v178, v108, v109
	v_cvt_pk_bf16_f32 v179, v110, v111
	v_mfma_f32_16x16x32_bf16 v[244:247], v[224:227], v[16:19], v[244:247]
	v_exp_f32_e32 v232, v232
	ds_read_b128 v[224:227], v160 offset:47168
	v_mfma_f32_16x16x32_bf16 v[236:239], v[228:231], v[8:11], v[236:239]
	v_exp_f32_e32 v233, v233
	v_mfma_f32_16x16x32_bf16 v[244:247], v[228:231], v[20:23], v[244:247]
	v_exp_f32_e32 v234, v234
	ds_read_b128 v[228:231], v165 offset:21504
	v_mfma_f32_16x16x32_bf16 v[84:87], v[44:47], v[168:171], v[84:87]
	v_exp_f32_e32 v235, v235
	v_mfma_f32_16x16x32_bf16 v[68:71], v[44:47], v[176:179], v[68:71]
	v_cvt_pk_bf16_f32 v232, v232, v233
	v_cvt_pk_bf16_f32 v233, v234, v235
	ds_read_b128 v[44:47], v165 offset:21568
	s_waitcnt lgkmcnt(3)
	v_mfma_f32_16x16x32_bf16 v[88:91], v[212:215], v[168:171], v[88:91]
	v_exp_f32_e32 v240, v240
	v_mfma_f32_16x16x32_bf16 v[72:75], v[212:215], v[176:179], v[72:75]
	v_exp_f32_e32 v241, v241
	ds_read_b128 v[212:215], v165 offset:21632
	v_mfma_f32_16x16x32_bf16 v[92:95], v[216:219], v[168:171], v[92:95]
	v_exp_f32_e32 v242, v242
	v_mfma_f32_16x16x32_bf16 v[76:79], v[216:219], v[176:179], v[76:79]
	v_exp_f32_e32 v243, v243
	ds_read_b128 v[216:219], v165 offset:25088
	v_mfma_f32_16x16x32_bf16 v[96:99], v[220:223], v[168:171], v[96:99]
	v_cvt_pk_bf16_f32 v240, v240, v241
	v_cvt_pk_bf16_f32 v241, v242, v243
	v_mfma_f32_16x16x32_bf16 v[80:83], v[220:223], v[176:179], v[80:83]
	v_exp_f32_e32 v236, v236
	ds_read_b128 v[220:223], v165 offset:25152
	s_waitcnt lgkmcnt(3)
	v_mfma_f32_16x16x32_bf16 v[104:107], v[224:227], v[168:171], v[104:107]
	v_exp_f32_e32 v237, v237
	v_mfma_f32_16x16x32_bf16 v[100:103], v[224:227], v[176:179], v[100:103]
	v_exp_f32_e32 v238, v238
	ds_read_b128 v[224:227], v165 offset:25216
	v_mfma_f32_16x16x32_bf16 v[168:171], v[228:231], v[0:3], 0
	v_exp_f32_e32 v239, v239
	v_mfma_f32_16x16x32_bf16 v[176:179], v[228:231], v[12:15], 0
	v_cvt_pk_bf16_f32 v234, v236, v237
	v_cvt_pk_bf16_f32 v235, v238, v239
	ds_read_b128 v[228:231], v160 offset:28800
	v_mfma_f32_16x16x32_bf16 v[168:171], v[44:47], v[4:7], v[168:171]
	v_exp_f32_e32 v244, v244
	v_mfma_f32_16x16x32_bf16 v[176:179], v[44:47], v[16:19], v[176:179]
	v_exp_f32_e32 v245, v245
	ds_read_b128 v[44:47], v160 offset:33408
	s_waitcnt lgkmcnt(3)
	v_mfma_f32_16x16x32_bf16 v[168:171], v[212:215], v[8:11], v[168:171]
	v_exp_f32_e32 v246, v246
	v_mfma_f32_16x16x32_bf16 v[176:179], v[212:215], v[20:23], v[176:179]
	v_exp_f32_e32 v247, v247
	ds_read_b128 v[212:215], v160 offset:38016
	v_mfma_f32_16x16x32_bf16 v[172:175], v[216:219], v[0:3], 0
	v_cvt_pk_bf16_f32 v242, v244, v245
	v_cvt_pk_bf16_f32 v243, v246, v247
	v_mfma_f32_16x16x32_bf16 v[108:111], v[216:219], v[12:15], 0
	ds_read_b128 v[216:219], v160 offset:42624
	v_mfma_f32_16x16x32_bf16 v[172:175], v[220:223], v[4:7], v[172:175]
	v_exp_f32_e32 v168, v168
	v_mfma_f32_16x16x32_bf16 v[108:111], v[220:223], v[16:19], v[108:111]
	v_exp_f32_e32 v169, v169
	ds_read_b128 v[220:223], v160 offset:47232
	s_waitcnt lgkmcnt(3)
	v_mfma_f32_16x16x32_bf16 v[172:175], v[224:227], v[8:11], v[172:175]
	v_exp_f32_e32 v170, v170
	v_mfma_f32_16x16x32_bf16 v[108:111], v[224:227], v[20:23], v[108:111]
	v_exp_f32_e32 v171, v171
	ds_read_b128 v[224:227], v160 offset:28864
	v_mfma_f32_16x16x32_bf16 v[84:87], v[228:231], v[232:235], v[84:87]
	v_cvt_pk_bf16_f32 v168, v168, v169
	v_cvt_pk_bf16_f32 v169, v170, v171
	v_mfma_f32_16x16x32_bf16 v[68:71], v[228:231], v[240:243], v[68:71]
	v_exp_f32_e32 v176, v176
	ds_read_b128 v[228:231], v160 offset:33472
	v_mfma_f32_16x16x32_bf16 v[88:91], v[44:47], v[232:235], v[88:91]
	v_exp_f32_e32 v177, v177
	v_mfma_f32_16x16x32_bf16 v[72:75], v[44:47], v[240:243], v[72:75]
	v_exp_f32_e32 v178, v178
	ds_read_b128 v[44:47], v160 offset:38080
	s_waitcnt lgkmcnt(3)
	v_mfma_f32_16x16x32_bf16 v[92:95], v[212:215], v[232:235], v[92:95]
	v_exp_f32_e32 v179, v179
	v_mfma_f32_16x16x32_bf16 v[76:79], v[212:215], v[240:243], v[76:79]
	v_cvt_pk_bf16_f32 v176, v176, v177
	v_cvt_pk_bf16_f32 v177, v178, v179
	ds_read_b128 v[212:215], v160 offset:42688
	v_mfma_f32_16x16x32_bf16 v[96:99], v[216:219], v[232:235], v[96:99]
	v_exp_f32_e32 v172, v172
	v_mfma_f32_16x16x32_bf16 v[80:83], v[216:219], v[240:243], v[80:83]
	v_exp_f32_e32 v173, v173
	ds_read_b128 v[216:219], v160 offset:47296
	v_mfma_f32_16x16x32_bf16 v[104:107], v[220:223], v[232:235], v[104:107]
	v_exp_f32_e32 v174, v174
	v_mfma_f32_16x16x32_bf16 v[100:103], v[220:223], v[240:243], v[100:103]
	v_exp_f32_e32 v175, v175
	s_waitcnt lgkmcnt(4)
	v_cvt_pk_bf16_f32 v170, v172, v173
	v_cvt_pk_bf16_f32 v171, v174, v175
	v_exp_f32_e32 v108, v108
	v_exp_f32_e32 v109, v109
	v_mfma_f32_16x16x32_bf16 v[84:87], v[224:227], v[168:171], v[84:87]
	v_exp_f32_e32 v110, v110
	s_waitcnt lgkmcnt(3)
	v_mfma_f32_16x16x32_bf16 v[88:91], v[228:231], v[168:171], v[88:91]
	v_exp_f32_e32 v111, v111
	s_waitcnt lgkmcnt(2)
	v_mfma_f32_16x16x32_bf16 v[92:95], v[44:47], v[168:171], v[92:95]
	v_cvt_pk_bf16_f32 v178, v108, v109
	v_cvt_pk_bf16_f32 v179, v110, v111
	s_waitcnt lgkmcnt(1)
	v_mfma_f32_16x16x32_bf16 v[96:99], v[212:215], v[168:171], v[96:99]
	s_waitcnt lgkmcnt(0)
	v_mfma_f32_16x16x32_bf16 v[104:107], v[216:219], v[168:171], v[104:107]
	v_mfma_f32_16x16x32_bf16 v[68:71], v[224:227], v[176:179], v[68:71]
	v_mfma_f32_16x16x32_bf16 v[72:75], v[228:231], v[176:179], v[72:75]
	v_mfma_f32_16x16x32_bf16 v[76:79], v[44:47], v[176:179], v[76:79]
	v_mfma_f32_16x16x32_bf16 v[80:83], v[212:215], v[176:179], v[80:83]
	v_mfma_f32_16x16x32_bf16 v[100:103], v[216:219], v[176:179], v[100:103]
	s_cmp_eq_u32 s53, 34
	s_cbranch_scc1 .LBB0_1504

.LBB0_1487:
	s_or_b32 s18, s54, 1
	s_or_b32 s16, s54, 2
	s_or_b32 s17, s54, 3
	v_cmp_le_u32_e32 vcc, s17, v248
	v_cmp_le_u32_e64 s[16:17], s16, v248
	v_cmp_le_u32_e64 s[18:19], s18, v248
	v_cmp_le_u32_e64 s[20:21], s54, v248
	s_and_saveexec_b64 s[38:39], s[20:21]
	s_cbranch_execz .LBB0_1491
	s_movk_i32 s20, 0x88
	v_cmp_gt_u32_e64 s[20:21], s20, v108
	s_nop 1
	v_cndmask_b32_e64 v110, 0, v200, s[20:21]
	ds_write_b16 v109, v110
	s_or_b64 exec, exec, s[38:39]
	s_and_saveexec_b64 s[20:21], s[18:19]
	s_cbranch_execnz .LBB0_1492
